# P2 BA tail loads batched; P5 pass-3 gate rows loaded at item top; P7 waves 4-7 use token groups 2,4,2 so read and write bursts interleave
# speedup vs baseline: 1.0052x; 1.0052x over previous
.LBB0_240:
	v_add_co_u32_e32 v154, vcc, 0x8b4000, v10
	v_mov_b32_e32 v152, v16
	v_mov_b32_e32 v153, v17
	s_nop 0
	v_addc_co_u32_e32 v155, vcc, 0, v11, vcc
	global_load_dwordx4 v[20:23], v[152:153], off
	global_load_dwordx4 v[84:87], v[154:155], off
	global_load_dwordx4 v[24:27], v[152:153], off offset:64
	global_load_dwordx4 v[88:91], v[154:155], off offset:64
	global_load_dwordx4 v[28:31], v[152:153], off offset:128
	global_load_dwordx4 v[92:95], v[154:155], off offset:128
	global_load_dwordx4 v[32:35], v[152:153], off offset:192
	global_load_dwordx4 v[96:99], v[154:155], off offset:192
	global_load_dwordx4 v[36:39], v[152:153], off offset:256
	global_load_dwordx4 v[100:103], v[154:155], off offset:256
	global_load_dwordx4 v[40:43], v[152:153], off offset:320
	global_load_dwordx4 v[104:107], v[154:155], off offset:320
	global_load_dwordx4 v[44:47], v[152:153], off offset:384
	global_load_dwordx4 v[108:111], v[154:155], off offset:384
	global_load_dwordx4 v[48:51], v[152:153], off offset:448
	global_load_dwordx4 v[112:115], v[154:155], off offset:448
	global_load_dwordx4 v[52:55], v[152:153], off offset:512
	global_load_dwordx4 v[116:119], v[154:155], off offset:512
	global_load_dwordx4 v[56:59], v[152:153], off offset:576
	global_load_dwordx4 v[120:123], v[154:155], off offset:576
	global_load_dwordx4 v[60:63], v[152:153], off offset:640
	global_load_dwordx4 v[124:127], v[154:155], off offset:640
	global_load_dwordx4 v[64:67], v[152:153], off offset:704
	global_load_dwordx4 v[128:131], v[154:155], off offset:704
	global_load_dwordx4 v[68:71], v[152:153], off offset:768
	global_load_dwordx4 v[132:135], v[154:155], off offset:768
	global_load_dwordx4 v[72:75], v[152:153], off offset:832
	global_load_dwordx4 v[136:139], v[154:155], off offset:832
	global_load_dwordx4 v[76:79], v[152:153], off offset:896
	global_load_dwordx4 v[140:143], v[154:155], off offset:896
	global_load_dwordx4 v[80:83], v[152:153], off offset:960
	global_load_dwordx4 v[144:147], v[154:155], off offset:960
	s_waitcnt vmcnt(30)
	v_mfma_f32_16x16x32_bf16 v[2:5], v[20:23], v[84:87], v[2:5]
	global_load_dwordx4 v[20:23], v[152:153], off offset:1024
	global_load_dwordx4 v[84:87], v[154:155], off offset:1024
	s_waitcnt vmcnt(30)
	v_mfma_f32_16x16x32_bf16 v[2:5], v[24:27], v[88:91], v[2:5]
	global_load_dwordx4 v[24:27], v[152:153], off offset:1088
	global_load_dwordx4 v[88:91], v[154:155], off offset:1088
	s_waitcnt vmcnt(30)
	v_mfma_f32_16x16x32_bf16 v[2:5], v[28:31], v[92:95], v[2:5]
	global_load_dwordx4 v[28:31], v[152:153], off offset:1152
	global_load_dwordx4 v[92:95], v[154:155], off offset:1152
	s_waitcnt vmcnt(30)
	v_mfma_f32_16x16x32_bf16 v[2:5], v[32:35], v[96:99], v[2:5]
	global_load_dwordx4 v[32:35], v[152:153], off offset:1216
	global_load_dwordx4 v[96:99], v[154:155], off offset:1216
	s_waitcnt vmcnt(30)
	v_mfma_f32_16x16x32_bf16 v[2:5], v[36:39], v[100:103], v[2:5]
	global_load_dwordx4 v[36:39], v[152:153], off offset:1280
	global_load_dwordx4 v[100:103], v[154:155], off offset:1280
	s_waitcnt vmcnt(30)
	v_mfma_f32_16x16x32_bf16 v[2:5], v[40:43], v[104:107], v[2:5]
	global_load_dwordx4 v[40:43], v[152:153], off offset:1344
	global_load_dwordx4 v[104:107], v[154:155], off offset:1344
	s_waitcnt vmcnt(30)
	v_mfma_f32_16x16x32_bf16 v[2:5], v[44:47], v[108:111], v[2:5]
	global_load_dwordx4 v[44:47], v[152:153], off offset:1408
	global_load_dwordx4 v[108:111], v[154:155], off offset:1408
	s_waitcnt vmcnt(30)
	v_mfma_f32_16x16x32_bf16 v[2:5], v[48:51], v[112:115], v[2:5]
	global_load_dwordx4 v[48:51], v[152:153], off offset:1472
	global_load_dwordx4 v[112:115], v[154:155], off offset:1472
	s_waitcnt vmcnt(30)
	v_mfma_f32_16x16x32_bf16 v[2:5], v[52:55], v[116:119], v[2:5]
	global_load_dwordx4 v[52:55], v[152:153], off offset:1536
	global_load_dwordx4 v[116:119], v[154:155], off offset:1536
	s_waitcnt vmcnt(30)
	v_mfma_f32_16x16x32_bf16 v[2:5], v[56:59], v[120:123], v[2:5]
	global_load_dwordx4 v[56:59], v[152:153], off offset:1600
	global_load_dwordx4 v[120:123], v[154:155], off offset:1600
	s_waitcnt vmcnt(30)
	v_mfma_f32_16x16x32_bf16 v[2:5], v[60:63], v[124:127], v[2:5]
	global_load_dwordx4 v[60:63], v[152:153], off offset:1664
	global_load_dwordx4 v[124:127], v[154:155], off offset:1664
	s_waitcnt vmcnt(30)
	v_mfma_f32_16x16x32_bf16 v[2:5], v[64:67], v[128:131], v[2:5]
	global_load_dwordx4 v[64:67], v[152:153], off offset:1728
	global_load_dwordx4 v[128:131], v[154:155], off offset:1728
	s_waitcnt vmcnt(30)
	v_mfma_f32_16x16x32_bf16 v[2:5], v[68:71], v[132:135], v[2:5]
	global_load_dwordx4 v[68:71], v[152:153], off offset:1792
	global_load_dwordx4 v[132:135], v[154:155], off offset:1792
	s_waitcnt vmcnt(30)
	v_mfma_f32_16x16x32_bf16 v[2:5], v[72:75], v[136:139], v[2:5]
	global_load_dwordx4 v[72:75], v[152:153], off offset:1856
	global_load_dwordx4 v[136:139], v[154:155], off offset:1856
	s_waitcnt vmcnt(30)
	v_mfma_f32_16x16x32_bf16 v[2:5], v[76:79], v[140:143], v[2:5]
	global_load_dwordx4 v[76:79], v[152:153], off offset:1920
	global_load_dwordx4 v[140:143], v[154:155], off offset:1920
	s_waitcnt vmcnt(30)
	v_mfma_f32_16x16x32_bf16 v[2:5], v[80:83], v[144:147], v[2:5]
	global_load_dwordx4 v[80:83], v[152:153], off offset:1984
	global_load_dwordx4 v[144:147], v[154:155], off offset:1984
	s_waitcnt vmcnt(30)
	v_mfma_f32_16x16x32_bf16 v[2:5], v[20:23], v[84:87], v[2:5]
	s_waitcnt vmcnt(28)
	v_mfma_f32_16x16x32_bf16 v[2:5], v[24:27], v[88:91], v[2:5]
	s_waitcnt vmcnt(26)
	v_mfma_f32_16x16x32_bf16 v[2:5], v[28:31], v[92:95], v[2:5]
	s_waitcnt vmcnt(24)
	v_mfma_f32_16x16x32_bf16 v[2:5], v[32:35], v[96:99], v[2:5]
	s_waitcnt vmcnt(22)
	v_mfma_f32_16x16x32_bf16 v[2:5], v[36:39], v[100:103], v[2:5]
	s_waitcnt vmcnt(20)
	v_mfma_f32_16x16x32_bf16 v[2:5], v[40:43], v[104:107], v[2:5]
	s_waitcnt vmcnt(18)
	v_mfma_f32_16x16x32_bf16 v[2:5], v[44:47], v[108:111], v[2:5]
	s_waitcnt vmcnt(16)
	v_mfma_f32_16x16x32_bf16 v[2:5], v[48:51], v[112:115], v[2:5]
	s_waitcnt vmcnt(14)
	v_mfma_f32_16x16x32_bf16 v[2:5], v[52:55], v[116:119], v[2:5]
	s_waitcnt vmcnt(12)
	v_mfma_f32_16x16x32_bf16 v[2:5], v[56:59], v[120:123], v[2:5]
	s_waitcnt vmcnt(10)
	v_mfma_f32_16x16x32_bf16 v[2:5], v[60:63], v[124:127], v[2:5]
	s_waitcnt vmcnt(8)
	v_mfma_f32_16x16x32_bf16 v[2:5], v[64:67], v[128:131], v[2:5]
	s_waitcnt vmcnt(6)
	v_mfma_f32_16x16x32_bf16 v[2:5], v[68:71], v[132:135], v[2:5]
	s_waitcnt vmcnt(4)
	v_mfma_f32_16x16x32_bf16 v[2:5], v[72:75], v[136:139], v[2:5]
	s_waitcnt vmcnt(2)
	v_mfma_f32_16x16x32_bf16 v[2:5], v[76:79], v[140:143], v[2:5]
	s_waitcnt vmcnt(0)
	v_mfma_f32_16x16x32_bf16 v[2:5], v[80:83], v[144:147], v[2:5]
	s_lshl_b32 s0, s4, 6
	s_add_i32 s0, s0, s2
	v_or_b32_e32 v16, s0, v18
	v_ashrrev_i32_e32 v17, 31, v16
	v_lshlrev_b64 v[20:21], 7, v[16:17]
	v_lshl_add_u64 v[20:21], v[8:9], 0, v[20:21]
	s_nop 0
	global_store_dword v[20:21], v2, off
	v_or_b32_e32 v20, 1, v16
	v_ashrrev_i32_e32 v21, 31, v20
	v_lshlrev_b64 v[20:21], 7, v[20:21]
	v_lshl_add_u64 v[20:21], v[8:9], 0, v[20:21]
	v_or_b32_e32 v2, 2, v16
	global_store_dword v[20:21], v3, off
	v_ashrrev_i32_e32 v3, 31, v2
	v_lshlrev_b64 v[2:3], 7, v[2:3]
	v_lshl_add_u64 v[2:3], v[8:9], 0, v[2:3]
	global_store_dword v[2:3], v4, off
	v_or_b32_e32 v2, 3, v16
	v_ashrrev_i32_e32 v3, 31, v2
	v_lshlrev_b64 v[2:3], 7, v[2:3]
	s_add_i32 s4, s4, s70
	v_lshl_add_u64 v[2:3], v[8:9], 0, v[2:3]
	s_cmpk_gt_i32 s4, 0xff
	v_add_u32_e32 v14, s3, v14
	global_store_dword v[2:3], v5, off
	s_cbranch_scc0 .LBB0_239

.LBB0_796:
	s_or_b64 exec, exec, s[12:13]
	s_waitcnt lgkmcnt(0)
	v_cndmask_b32_e64 v4, v11, 1.0, s[10:11]
	v_mul_f32_e32 v8, v4, v13
	v_cndmask_b32_e64 v4, v4, v8, s[6:7]
	v_mul_f32_e32 v8, v4, v9
	v_cndmask_b32_e64 v4, v4, v8, s[4:5]
	v_cndmask_b32_e64 v8, v62, 0, s[10:11]
	v_fmac_f32_e32 v63, v8, v13
	v_cndmask_b32_e64 v8, v8, v63, s[6:7]
	v_fmac_f32_e32 v10, v8, v9
	v_cndmask_b32_e64 v8, v8, v10, s[4:5]
	v_fmac_f32_e32 v8, v4, v64
	v_cndmask_b32_e64 v4, v204, 1.0, s[4:5]
	v_mul_f32_e32 v9, v4, v200
	v_cndmask_b32_e64 v4, v4, v9, s[8:9]
	v_mul_f32_e32 v9, v4, v198
	v_cndmask_b32_e64 v4, v4, v9, s[10:11]
	v_cndmask_b32_e64 v9, v202, 0, s[4:5]
	v_fmac_f32_e32 v201, v9, v200
	v_cndmask_b32_e64 v9, v9, v201, s[8:9]
	v_fmac_f32_e32 v199, v9, v198
	v_cndmask_b32_e64 v9, v9, v199, s[10:11]
	v_fmac_f32_e32 v9, v4, v230
	v_fmac_f32_e32 v196, v197, v9
	v_fmac_f32_e32 v5, v20, v8
	v_add_f32_e32 v4, 0, v196
	v_fmac_f32_e32 v194, v195, v9
	v_add_f32_e32 v4, v4, v5
	v_fmac_f32_e32 v2, v21, v8
	v_add_f32_e32 v5, 0, v194
	v_fmac_f32_e32 v192, v193, v9
	v_add_f32_e32 v2, v5, v2
	v_fmac_f32_e32 v6, v22, v8
	v_add_f32_e32 v5, 0, v192
	v_fmac_f32_e32 v191, v190, v9
	v_add_f32_e32 v5, v5, v6
	v_fmac_f32_e32 v7, v23, v8
	v_add_f32_e32 v6, 0, v191
	v_add_f32_e32 v6, v6, v7
	v_cndmask_b32_e64 v7, v60, 1.0, s[10:11]
	v_mul_f32_e32 v8, v7, v55
	v_cndmask_b32_e64 v7, v7, v8, s[6:7]
	v_mul_f32_e32 v8, v7, v56
	v_cndmask_b32_e64 v7, v7, v8, s[4:5]
	v_cndmask_b32_e64 v8, v59, 0, s[10:11]
	v_fmac_f32_e32 v58, v8, v55
	v_cndmask_b32_e64 v8, v8, v58, s[6:7]
	v_fmac_f32_e32 v57, v8, v56
	v_cndmask_b32_e64 v8, v8, v57, s[4:5]
	v_fmac_f32_e32 v8, v7, v61
	v_cndmask_b32_e64 v7, v229, 1.0, s[4:5]
	v_mul_f32_e32 v9, v7, v226
	v_cndmask_b32_e64 v7, v7, v9, s[8:9]
	v_mul_f32_e32 v9, v7, v224
	v_cndmask_b32_e64 v7, v7, v9, s[10:11]
	v_cndmask_b32_e64 v9, v228, 0, s[4:5]
	v_fmac_f32_e32 v227, v9, v226
	v_cndmask_b32_e64 v9, v9, v227, s[8:9]
	v_fmac_f32_e32 v225, v9, v224
	v_cndmask_b32_e64 v9, v9, v225, s[10:11]
	v_fmac_f32_e32 v9, v7, v189
	v_fmac_f32_e32 v222, v223, v9
	v_fmac_f32_e32 v220, v221, v9
	v_fmac_f32_e32 v212, v213, v9
	v_fmac_f32_e32 v185, v184, v9
	v_cndmask_b32_e64 v9, v53, 1.0, s[10:11]
	v_mul_f32_e32 v12, v9, v48
	v_cndmask_b32_e64 v9, v9, v12, s[6:7]
	v_mul_f32_e32 v12, v9, v49
	v_cndmask_b32_e64 v9, v9, v12, s[4:5]
	v_cndmask_b32_e64 v12, v52, 0, s[10:11]
	v_fmac_f32_e32 v51, v12, v48
	v_cndmask_b32_e64 v12, v12, v51, s[6:7]
	v_fmac_f32_e32 v50, v12, v49
	v_cndmask_b32_e64 v12, v12, v50, s[4:5]
	v_fmac_f32_e32 v12, v9, v54
	v_cndmask_b32_e64 v9, v219, 1.0, s[4:5]
	v_mul_f32_e32 v13, v9, v216
	v_cndmask_b32_e64 v9, v9, v13, s[8:9]
	v_mul_f32_e32 v13, v9, v214
	v_cndmask_b32_e64 v9, v9, v13, s[10:11]
	v_cndmask_b32_e64 v13, v218, 0, s[4:5]
	v_fmac_f32_e32 v217, v13, v216
	v_cndmask_b32_e64 v13, v13, v217, s[8:9]
	v_fmac_f32_e32 v215, v13, v214
	v_cndmask_b32_e64 v13, v13, v215, s[10:11]
	v_fmac_f32_e32 v13, v9, v207
	v_fmac_f32_e32 v210, v211, v13
	v_fmac_f32_e32 v208, v209, v13
	v_fmac_f32_e32 v205, v206, v13
	v_fmac_f32_e32 v187, v186, v13
	v_cndmask_b32_e64 v13, v41, 1.0, s[10:11]
	v_fmac_f32_e32 v17, v16, v12
	v_mul_f32_e32 v16, v13, v37
	v_cndmask_b32_e64 v13, v13, v16, s[6:7]
	v_mul_f32_e32 v16, v13, v30
	v_cndmask_b32_e64 v13, v13, v16, s[4:5]
	v_cndmask_b32_e64 v16, v40, 0, s[10:11]
	v_fmac_f32_e32 v39, v16, v37
	v_cndmask_b32_e64 v16, v16, v39, s[6:7]
	v_fmac_f32_e32 v38, v16, v30
	v_cndmask_b32_e64 v16, v16, v38, s[4:5]
	v_fmac_f32_e32 v16, v3, v13
	v_cndmask_b32_e64 v3, v109, 1.0, s[4:5]
	v_mul_f32_e32 v13, v3, v105
	v_cndmask_b32_e64 v3, v3, v13, s[8:9]
	v_mul_f32_e32 v13, v3, v107
	v_cndmask_b32_e64 v3, v3, v13, s[10:11]
	v_cndmask_b32_e64 v13, v129, 0, s[4:5]
	v_fmac_f32_e32 v128, v13, v105
	v_cndmask_b32_e64 v13, v13, v128, s[8:9]
	v_fmac_f32_e32 v104, v13, v107
	v_cndmask_b32_e64 v13, v13, v104, s[10:11]
	v_fmac_f32_e32 v13, v3, v203
	v_add_f32_e32 v9, 0, v210
	v_fmac_f32_e32 v102, v103, v13
	v_fmac_f32_e32 v15, v14, v8
	v_add_f32_e32 v7, 0, v222
	v_add_f32_e32 v9, v9, v17
	v_fmac_f32_e32 v34, v36, v12
	v_add_f32_e32 v14, 0, v208
	v_fmac_f32_e32 v124, v125, v13
	v_fmac_f32_e32 v27, v29, v16
	v_add_f32_e32 v17, 0, v102
	v_fmac_f32_e32 v100, v101, v13
	v_fmac_f32_e32 v99, v188, v13
	v_add_f32_e32 v7, v7, v15
	v_fmac_f32_e32 v45, v47, v8
	v_add_f32_e32 v10, 0, v220
	v_fmac_f32_e32 v43, v46, v8
	v_add_f32_e32 v11, 0, v212
	v_fmac_f32_e32 v42, v44, v8
	v_add_f32_e32 v8, 0, v185
	v_add_f32_e32 v14, v14, v34
	v_fmac_f32_e32 v32, v35, v12
	v_add_f32_e32 v15, 0, v205
	v_fmac_f32_e32 v31, v33, v12
	v_add_f32_e32 v12, 0, v187
	v_fmac_f32_e32 v19, v18, v16
	v_add_f32_e32 v3, 0, v124
	v_add_f32_e32 v17, v17, v27
	v_fmac_f32_e32 v25, v28, v16
	v_add_f32_e32 v18, 0, v100
	v_fmac_f32_e32 v24, v26, v16
	v_add_f32_e32 v13, 0, v99
	v_add_f32_e32 v10, v10, v45
	v_add_f32_e32 v11, v11, v43
	v_add_f32_e32 v8, v8, v42
	v_add_f32_e32 v15, v15, v32
	v_add_f32_e32 v12, v12, v31
	v_add_f32_e32 v3, v3, v19
	v_add_f32_e32 v18, v18, v25
	v_add_f32_e32 v13, v13, v24
	ds_write2st64_b32 v143, v6, v5 offset0:196 offset1:198
	ds_write2st64_b32 v143, v2, v4 offset0:200 offset1:202
	ds_write2st64_b32 v143, v8, v11 offset0:228 offset1:230
	ds_write2st64_b32 v143, v10, v7 offset0:232 offset1:234
	ds_write_b32 v170, v12 offset:50176
	ds_write_b32 v171, v15 offset:50176
	ds_write_b32 v172, v14 offset:50176
	ds_write_b32 v173, v9 offset:50176
	ds_write_b32 v174, v13 offset:50176
	ds_write_b32 v175, v18 offset:50176
	ds_write_b32 v176, v17 offset:50176
	ds_write_b32 v177, v3 offset:50176
	v_or_b32_e32 v14, s52, v158
	v_mov_b64_e32 v[16:17], s[74:75]
	s_lshl_b32 s2, s53, 1
	v_lshlrev_b32_e32 v136, 1, v132
	s_waitcnt lgkmcnt(0)
	s_barrier
	s_nop 0
	v_ashrrev_i32_e32 v15, 31, v14
	s_add_i32 s51, s51, s70
	s_cmpk_gt_i32 s51, 0x3ff
	v_mov_b32_e32 v2, v240
	v_mov_b32_e32 v3, v241
	v_mov_b32_e32 v4, v242
	v_mov_b32_e32 v5, v243
	v_lshlrev_b32_e32 v18, 16, v2
	v_and_b32_e32 v19, 0xffff0000, v2
	v_mul_f32_e32 v2, 0xbfb8aa3b, v18
	v_exp_f32_e32 v2, v2
	v_mul_f32_e32 v6, 0xbfb8aa3b, v19
	v_exp_f32_e32 v6, v6
	v_add_f32_e32 v2, 1.0, v2
	v_rcp_f32_e32 v20, v2
	v_add_f32_e32 v2, 1.0, v6
	v_rcp_f32_e32 v21, v2
	ds_read_b128 v[6:9], v178 offset:50176
	ds_read_b128 v[10:13], v178 offset:50192
	v_pk_mul_f32 v[18:19], v[20:21], v[18:19]
	v_lshlrev_b32_e32 v20, 16, v4
	v_and_b32_e32 v21, 0xffff0000, v4
	v_mul_f32_e32 v2, 0xbfb8aa3b, v20
	v_exp_f32_e32 v2, v2
	v_mul_f32_e32 v4, 0xbfb8aa3b, v21
	v_exp_f32_e32 v4, v4
	s_waitcnt lgkmcnt(1)
	v_pk_mul_f32 v[6:7], v[6:7], v[18:19]
	v_add_f32_e32 v2, 1.0, v2
	v_rcp_f32_e32 v18, v2
	v_add_f32_e32 v2, 1.0, v4
	v_rcp_f32_e32 v19, v2
	v_lshlrev_b32_e32 v2, 16, v3
	v_and_b32_e32 v3, 0xffff0000, v3
	v_mul_f32_e32 v4, 0xbfb8aa3b, v2
	v_pk_mul_f32 v[18:19], v[18:19], v[20:21]
	v_lshlrev_b32_e32 v20, 16, v5
	v_mul_f32_e32 v22, 0xbfb8aa3b, v3
	v_and_b32_e32 v21, 0xffff0000, v5
	v_mul_f32_e32 v5, 0xbfb8aa3b, v20
	v_exp_f32_e32 v4, v4
	v_exp_f32_e32 v22, v22
	v_exp_f32_e32 v23, v5
	v_mul_f32_e32 v5, 0xbfb8aa3b, v21
	v_exp_f32_e32 v24, v5
	v_add_f32_e32 v4, 1.0, v4
	v_add_f32_e32 v22, 1.0, v22
	v_rcp_f32_e32 v4, v4
	v_rcp_f32_e32 v5, v22
	v_add_f32_e32 v22, 1.0, v23
	v_add_f32_e32 v23, 1.0, v24
	v_rcp_f32_e32 v22, v22
	v_rcp_f32_e32 v23, v23
	v_pk_mul_f32 v[2:3], v[4:5], v[2:3]
	s_waitcnt lgkmcnt(0)
	v_pk_mul_f32 v[10:11], v[10:11], v[18:19]
	v_pk_mul_f32 v[4:5], v[8:9], v[2:3]
	v_pk_mul_f32 v[2:3], v[22:23], v[20:21]
	s_nop 0
	v_pk_mul_f32 v[8:9], v[12:13], v[2:3]
	v_cvt_pk_bf16_f32 v2, v6, v7
	v_lshlrev_b64 v[6:7], 12, v[14:15]
	v_lshl_add_u64 v[6:7], s[72:73], 0, v[6:7]
	v_lshl_add_u64 v[6:7], v[6:7], 0, s[2:3]
	v_cvt_pk_bf16_f32 v3, v4, v5
	v_cvt_pk_bf16_f32 v4, v10, v11
	v_cvt_pk_bf16_f32 v5, v8, v9
	v_lshl_add_u64 v[6:7], v[6:7], 0, v[136:137]
	v_add_u32_e32 v14, s52, v163
	global_store_dwordx4 v[6:7], v[2:5], off offset:2048
	v_ashrrev_i32_e32 v15, 31, v14
	s_nop 0
	s_nop 0
	v_mov_b32_e32 v2, v244
	v_mov_b32_e32 v3, v245
	v_mov_b32_e32 v4, v246
	v_mov_b32_e32 v5, v247
	v_lshlrev_b32_e32 v16, 16, v2
	v_and_b32_e32 v17, 0xffff0000, v2
	v_mul_f32_e32 v2, 0xbfb8aa3b, v16
	v_exp_f32_e32 v2, v2
	v_mul_f32_e32 v6, 0xbfb8aa3b, v17
	v_exp_f32_e32 v6, v6
	v_add_f32_e32 v2, 1.0, v2
	v_rcp_f32_e32 v18, v2
	v_add_f32_e32 v2, 1.0, v6
	v_rcp_f32_e32 v19, v2
	ds_read_b128 v[6:9], v179 offset:50176
	ds_read_b128 v[10:13], v179 offset:50192
	v_pk_mul_f32 v[16:17], v[18:19], v[16:17]
	v_lshlrev_b32_e32 v18, 16, v4
	v_and_b32_e32 v19, 0xffff0000, v4
	v_mul_f32_e32 v2, 0xbfb8aa3b, v18
	v_exp_f32_e32 v2, v2
	v_mul_f32_e32 v4, 0xbfb8aa3b, v19
	v_exp_f32_e32 v4, v4
	s_waitcnt lgkmcnt(1)
	v_pk_mul_f32 v[6:7], v[6:7], v[16:17]
	v_add_f32_e32 v2, 1.0, v2
	v_rcp_f32_e32 v16, v2
	v_add_f32_e32 v2, 1.0, v4
	v_rcp_f32_e32 v17, v2
	v_lshlrev_b32_e32 v2, 16, v3
	v_and_b32_e32 v3, 0xffff0000, v3
	v_mul_f32_e32 v4, 0xbfb8aa3b, v2
	v_pk_mul_f32 v[16:17], v[16:17], v[18:19]
	v_lshlrev_b32_e32 v18, 16, v5
	v_mul_f32_e32 v20, 0xbfb8aa3b, v3
	v_and_b32_e32 v19, 0xffff0000, v5
	v_mul_f32_e32 v5, 0xbfb8aa3b, v18
	v_exp_f32_e32 v4, v4
	v_exp_f32_e32 v20, v20
	v_exp_f32_e32 v21, v5
	v_mul_f32_e32 v5, 0xbfb8aa3b, v19
	v_exp_f32_e32 v22, v5
	v_add_f32_e32 v4, 1.0, v4
	v_add_f32_e32 v20, 1.0, v20
	v_rcp_f32_e32 v4, v4
	v_rcp_f32_e32 v5, v20
	v_add_f32_e32 v20, 1.0, v21
	v_add_f32_e32 v21, 1.0, v22
	v_rcp_f32_e32 v20, v20
	v_rcp_f32_e32 v21, v21
	v_pk_mul_f32 v[2:3], v[4:5], v[2:3]
	s_waitcnt lgkmcnt(0)
	v_pk_mul_f32 v[10:11], v[10:11], v[16:17]
	v_pk_mul_f32 v[4:5], v[8:9], v[2:3]
	v_pk_mul_f32 v[2:3], v[20:21], v[18:19]
	s_nop 0
	v_pk_mul_f32 v[8:9], v[12:13], v[2:3]
	v_cvt_pk_bf16_f32 v2, v6, v7
	v_lshlrev_b64 v[6:7], 12, v[14:15]
	v_lshl_add_u64 v[6:7], s[72:73], 0, v[6:7]
	v_lshl_add_u64 v[6:7], v[6:7], 0, s[2:3]
	v_cvt_pk_bf16_f32 v3, v4, v5
	v_cvt_pk_bf16_f32 v4, v10, v11
	v_cvt_pk_bf16_f32 v5, v8, v9
	v_lshl_add_u64 v[6:7], v[6:7], 0, v[136:137]
	global_store_dwordx4 v[6:7], v[2:5], off offset:2048
	s_waitcnt lgkmcnt(0)
	s_barrier
	s_cbranch_scc1 .LBB0_819
.LBB0_797:
	s_ashr_i32 s39, s51, 3
	s_add_i32 s54, s39, 0x80
	s_and_b32 s2, s51, 7
	s_lshl_b32 s53, s2, 7
	s_lshl_b32 s52, s54, 6
	s_cmp_gt_i32 s39, -1
	s_cselect_b64 s[14:15], -1, 0
	s_and_b32 s38, s54, -4
	s_and_b32 s12, s54, 0x7fffffc0
	s_add_i32 s40, s38, 4
	s_add_i32 s13, s12, 64
	s_cmp_lt_i32 s39, 0
	s_cselect_b32 s13, s40, s13
	s_cselect_b32 s12, s38, s12
	v_or_b32_e32 v15, s52, v161
	v_add_u32_e32 v6, -2, v15
	s_lshl_b32 s36, s12, 6
	v_or_b32_e32 v251, s52, v158
	v_mov_b32_e32 v248, s74
	v_mov_b32_e32 v249, s75
	v_add_u32_e32 v240, s53, v132
	v_lshlrev_b32_e32 v240, 1, v240
	v_add_u32_e32 v240, s42, v240
	v_mov_b32_e32 v241, 0
	v_mad_i64_i32 v[248:249], vcc, v251, s33, v[248:249]
	v_lshl_add_u64 v[248:249], v[248:249], 0, v[240:241]
	global_load_dwordx4 v[240:243], v[248:249], off offset:2048
	v_add_u32_e32 v251, s52, v163
	v_mov_b32_e32 v246, s74
	v_mov_b32_e32 v247, s75
	v_add_u32_e32 v244, s53, v132
	v_lshlrev_b32_e32 v244, 1, v244
	v_add_u32_e32 v244, s42, v244
	v_mov_b32_e32 v245, 0
	v_mad_i64_i32 v[246:247], vcc, v251, s33, v[246:247]
	v_lshl_add_u64 v[246:247], v[246:247], 0, v[244:245]
	global_load_dwordx4 v[244:247], v[246:247], off offset:2048
	s_lshl_b32 s37, s13, 6
	v_or_b32_e32 v2, s53, v132
	v_cmp_le_i32_e32 vcc, s36, v6
	v_cmp_gt_i32_e64 s[12:13], s37, v6
	s_and_b64 s[56:57], vcc, s[12:13]
	v_lshlrev_b32_e32 v136, 1, v2
	v_mov_b32_e32 v2, 0
	v_mov_b32_e32 v3, 0
	v_mov_b32_e32 v4, 0
	v_mov_b32_e32 v5, 0
	s_and_saveexec_b64 s[12:13], s[56:57]
	s_cbranch_execz .LBB0_799
	v_mov_b64_e32 v[2:3], s[74:75]
	v_mad_i64_i32 v[2:3], s[56:57], v6, s33, v[2:3]
	v_lshl_add_u64 v[2:3], v[2:3], 0, v[136:137]
	v_add_co_u32_e32 v2, vcc, 0x39c6000, v2
	s_nop 1
	v_addc_co_u32_e32 v3, vcc, 0, v3, vcc
	global_load_dwordx4 v[2:5], v[2:3], off

.Lp7n_norow:
	s_waitcnt lgkmcnt(0)
	s_cmp_lt_u32 s97, 4
	s_cbranch_scc0 .Lp7n_pathB
	s_add_u32 s2, s21, 0
	s_mul_i32 s12, s2, 0x3000
	s_add_u32 s10, s74, 0x39c4000
	s_addc_u32 s11, s75, 0
	s_add_u32 s10, s10, s12
	s_addc_u32 s11, s11, 0
	global_load_dwordx2 v[148:149], v80, s[10:11] offset:0 nt
	global_load_dwordx2 v[150:151], v80, s[10:11] offset:512 nt
	global_load_dwordx2 v[152:153], v80, s[10:11] offset:1024 nt
	global_load_dwordx2 v[154:155], v80, s[10:11] offset:1536 nt
	s_cmpk_lt_u32 s2, 0x2000
	s_cselect_b32 s10, s4, s6
	s_cselect_b32 s11, s5, s7
	s_and_b32 s12, s2, 0x1fff
	s_lshl_b32 s12, s12, 12
	s_add_u32 s10, s10, s12
	s_addc_u32 s11, s11, 0
	global_load_dwordx4 v[84:87], v79, s[10:11] offset:0 nt
	global_load_dwordx4 v[88:91], v79, s[10:11] offset:1024 nt
	global_load_dwordx4 v[92:95], v79, s[10:11] offset:2048 nt
	global_load_dwordx4 v[96:99], v79, s[10:11] offset:3072 nt
	s_cmp_eq_u32 s28, 0
	s_cbranch_scc1 .Lp7n_nocol_a0
	s_and_b32 s12, s2, 63
	s_lshl_b32 s12, s12, 10
	s_add_u32 s10, s74, 0x94000
	s_addc_u32 s11, s75, 0
	s_add_u32 s10, s10, s12
	s_addc_u32 s11, s11, 0
	global_load_dwordx4 v[18:21], v79, s[10:11]
	s_add_u32 s10, s10, 0x10000
	s_addc_u32 s11, s11, 0
	global_load_dwordx4 v[22:25], v79, s[10:11]

.Lp7n_pathB:
	s_add_u32 s2, s21, 0
	s_mul_i32 s12, s2, 0x3000
	s_add_u32 s10, s74, 0x39c4000
	s_addc_u32 s11, s75, 0
	s_add_u32 s10, s10, s12
	s_addc_u32 s11, s11, 0
	global_load_dwordx2 v[148:149], v80, s[10:11] offset:0 nt
	global_load_dwordx2 v[150:151], v80, s[10:11] offset:512 nt
	global_load_dwordx2 v[152:153], v80, s[10:11] offset:1024 nt
	global_load_dwordx2 v[154:155], v80, s[10:11] offset:1536 nt
	s_cmpk_lt_u32 s2, 0x2000
	s_cselect_b32 s10, s4, s6
	s_cselect_b32 s11, s5, s7
	s_and_b32 s12, s2, 0x1fff
	s_lshl_b32 s12, s12, 12
	s_add_u32 s10, s10, s12
	s_addc_u32 s11, s11, 0
	global_load_dwordx4 v[84:87], v79, s[10:11] offset:0 nt
	global_load_dwordx4 v[88:91], v79, s[10:11] offset:1024 nt
	global_load_dwordx4 v[92:95], v79, s[10:11] offset:2048 nt
	global_load_dwordx4 v[96:99], v79, s[10:11] offset:3072 nt
	s_cmp_eq_u32 s28, 0
	s_cbranch_scc1 .Lp7n_nocol_b0
	s_and_b32 s12, s2, 63
	s_lshl_b32 s12, s12, 10
	s_add_u32 s10, s74, 0x94000
	s_addc_u32 s11, s75, 0
	s_add_u32 s10, s10, s12
	s_addc_u32 s11, s11, 0
	global_load_dwordx4 v[18:21], v79, s[10:11]
	s_add_u32 s10, s10, 0x10000
	s_addc_u32 s11, s11, 0
	global_load_dwordx4 v[22:25], v79, s[10:11]
.Lp7n_nocol_b0:
	s_add_u32 s2, s21, 1
	s_mul_i32 s12, s2, 0x3000
	s_add_u32 s10, s74, 0x39c4000
	s_addc_u32 s11, s75, 0
	s_add_u32 s10, s10, s12
	s_addc_u32 s11, s11, 0
	global_load_dwordx2 v[156:157], v80, s[10:11] offset:0 nt
	global_load_dwordx2 v[158:159], v80, s[10:11] offset:512 nt
	global_load_dwordx2 v[160:161], v80, s[10:11] offset:1024 nt
	global_load_dwordx2 v[162:163], v80, s[10:11] offset:1536 nt
	s_cmpk_lt_u32 s2, 0x2000
	s_cselect_b32 s10, s4, s6
	s_cselect_b32 s11, s5, s7
	s_and_b32 s12, s2, 0x1fff
	s_lshl_b32 s12, s12, 12
	s_add_u32 s10, s10, s12
	s_addc_u32 s11, s11, 0
	global_load_dwordx4 v[100:103], v79, s[10:11] offset:0 nt
	global_load_dwordx4 v[104:107], v79, s[10:11] offset:1024 nt
	global_load_dwordx4 v[108:111], v79, s[10:11] offset:2048 nt
	global_load_dwordx4 v[112:115], v79, s[10:11] offset:3072 nt
	s_cmp_eq_u32 s28, 0
	s_cbranch_scc1 .Lp7n_nocol_b1
	s_and_b32 s12, s2, 63
	s_lshl_b32 s12, s12, 10
	s_add_u32 s10, s74, 0x94000
	s_addc_u32 s11, s75, 0
	s_add_u32 s10, s10, s12
	s_addc_u32 s11, s11, 0
	global_load_dwordx4 v[26:29], v79, s[10:11]
	s_add_u32 s10, s10, 0x10000
	s_addc_u32 s11, s11, 0
	global_load_dwordx4 v[30:33], v79, s[10:11]
.Lp7n_nocol_b1:
	s_waitcnt vmcnt(0)
	s_cmp_eq_u32 s28, 0
	s_cbranch_scc1 .Lp7n_nope_b0
	v_pk_add_f32 v[84:85], v[84:85], v[62:63]
	v_pk_add_f32 v[86:87], v[86:87], v[64:65]
	v_pk_add_f32 v[88:89], v[88:89], v[66:67]
	v_pk_add_f32 v[90:91], v[90:91], v[68:69]
	v_pk_add_f32 v[92:93], v[92:93], v[18:19]
	v_pk_add_f32 v[94:95], v[94:95], v[20:21]
	v_pk_add_f32 v[96:97], v[96:97], v[22:23]
	v_pk_add_f32 v[98:99], v[98:99], v[24:25]
	v_pk_add_f32 v[100:101], v[100:101], v[62:63]
	v_pk_add_f32 v[102:103], v[102:103], v[64:65]
	v_pk_add_f32 v[104:105], v[104:105], v[66:67]
	v_pk_add_f32 v[106:107], v[106:107], v[68:69]
	v_pk_add_f32 v[108:109], v[108:109], v[26:27]
	v_pk_add_f32 v[110:111], v[110:111], v[28:29]
	v_pk_add_f32 v[112:113], v[112:113], v[30:31]
	v_pk_add_f32 v[114:115], v[114:115], v[32:33]
.Lp7n_nope_b0:
	v_lshlrev_b32_e32 v180, 16, v148
	v_and_b32_e32 v181, 0xffff0000, v148
	v_lshlrev_b32_e32 v182, 16, v149
	v_and_b32_e32 v183, 0xffff0000, v149
	v_lshlrev_b32_e32 v184, 16, v150
	v_and_b32_e32 v185, 0xffff0000, v150
	v_lshlrev_b32_e32 v186, 16, v151
	v_and_b32_e32 v187, 0xffff0000, v151
	v_lshlrev_b32_e32 v188, 16, v152
	v_and_b32_e32 v189, 0xffff0000, v152
	v_lshlrev_b32_e32 v190, 16, v153
	v_and_b32_e32 v191, 0xffff0000, v153
	v_lshlrev_b32_e32 v192, 16, v154
	v_and_b32_e32 v193, 0xffff0000, v154
	v_lshlrev_b32_e32 v194, 16, v155
	v_and_b32_e32 v195, 0xffff0000, v155
	v_lshlrev_b32_e32 v196, 16, v156
	v_and_b32_e32 v197, 0xffff0000, v156
	v_lshlrev_b32_e32 v198, 16, v157
	v_and_b32_e32 v199, 0xffff0000, v157
	v_lshlrev_b32_e32 v200, 16, v158
	v_and_b32_e32 v201, 0xffff0000, v158
	v_lshlrev_b32_e32 v202, 16, v159
	v_and_b32_e32 v203, 0xffff0000, v159
	v_lshlrev_b32_e32 v204, 16, v160
	v_and_b32_e32 v205, 0xffff0000, v160
	v_lshlrev_b32_e32 v206, 16, v161
	v_and_b32_e32 v207, 0xffff0000, v161
	v_lshlrev_b32_e32 v208, 16, v162
	v_and_b32_e32 v209, 0xffff0000, v162
	v_lshlrev_b32_e32 v210, 16, v163
	v_and_b32_e32 v211, 0xffff0000, v163
	v_pk_mul_f32 v[148:149], v[180:181], v[180:181]
	v_pk_mul_f32 v[156:157], v[196:197], v[196:197]
	v_pk_fma_f32 v[148:149], v[182:183], v[182:183], v[148:149]
	v_pk_fma_f32 v[156:157], v[198:199], v[198:199], v[156:157]
	v_pk_fma_f32 v[148:149], v[184:185], v[184:185], v[148:149]
	v_pk_fma_f32 v[156:157], v[200:201], v[200:201], v[156:157]
	v_pk_fma_f32 v[148:149], v[186:187], v[186:187], v[148:149]
	v_pk_fma_f32 v[156:157], v[202:203], v[202:203], v[156:157]
	v_pk_fma_f32 v[148:149], v[188:189], v[188:189], v[148:149]
	v_pk_fma_f32 v[156:157], v[204:205], v[204:205], v[156:157]
	v_pk_fma_f32 v[148:149], v[190:191], v[190:191], v[148:149]
	v_pk_fma_f32 v[156:157], v[206:207], v[206:207], v[156:157]
	v_pk_fma_f32 v[148:149], v[192:193], v[192:193], v[148:149]
	v_pk_fma_f32 v[156:157], v[208:209], v[208:209], v[156:157]
	v_pk_fma_f32 v[148:149], v[194:195], v[194:195], v[148:149]
	v_pk_fma_f32 v[156:157], v[210:211], v[210:211], v[156:157]
	v_add_f32_e32 v148, v148, v149
	v_add_f32_e32 v156, v156, v157
	ds_bpermute_b32 v149, v35, v148
	ds_bpermute_b32 v157, v35, v156
	s_waitcnt lgkmcnt(0)
	v_add_f32_e32 v148, v148, v149
	v_add_f32_e32 v156, v156, v157
	ds_bpermute_b32 v149, v70, v148
	ds_bpermute_b32 v157, v70, v156
	s_waitcnt lgkmcnt(0)
	v_add_f32_e32 v148, v148, v149
	v_add_f32_e32 v156, v156, v157
	ds_bpermute_b32 v149, v71, v148
	ds_bpermute_b32 v157, v71, v156
	s_waitcnt lgkmcnt(0)
	v_add_f32_e32 v148, v148, v149
	v_add_f32_e32 v156, v156, v157
	ds_bpermute_b32 v149, v72, v148
	ds_bpermute_b32 v157, v72, v156
	s_waitcnt lgkmcnt(0)
	v_add_f32_e32 v148, v148, v149
	v_add_f32_e32 v156, v156, v157
	ds_bpermute_b32 v149, v73, v148
	ds_bpermute_b32 v157, v73, v156
	s_waitcnt lgkmcnt(0)
	v_add_f32_e32 v148, v148, v149
	v_add_f32_e32 v156, v156, v157
	ds_bpermute_b32 v149, v74, v148
	ds_bpermute_b32 v157, v74, v156
	s_waitcnt lgkmcnt(0)
	v_add_f32_e32 v148, v148, v149
	v_add_f32_e32 v156, v156, v157
	v_fmamk_f32 v148, v148, 0x3a800000, v77
	v_fmamk_f32 v156, v156, 0x3a800000, v77
	v_mul_f32_e32 v150, 0x4b800000, v148
	v_cmp_gt_f32_e32 vcc, s26, v148
	s_nop 1
	v_cndmask_b32_e32 v148, v148, v150, vcc
	v_rsq_f32_e32 v148, v148
	s_nop 0
	v_mul_f32_e32 v150, 0x45800000, v148
	v_cndmask_b32_e32 v148, v148, v150, vcc
	v_mul_f32_e32 v158, 0x4b800000, v156
	v_cmp_gt_f32_e32 vcc, s26, v156
	s_nop 1
	v_cndmask_b32_e32 v156, v156, v158, vcc
	v_rsq_f32_e32 v156, v156
	s_nop 0
	v_mul_f32_e32 v158, 0x45800000, v156
	v_cndmask_b32_e32 v156, v156, v158, vcc
	s_add_u32 s2, s21, 0
	s_lshl_b32 s2, s2, 12
	s_add_u32 s10, s72, s2
	s_addc_u32 s11, s73, 0
	v_pk_mul_f32 v[180:181], v[180:181], v[148:149] op_sel_hi:[1,0]
	v_pk_mul_f32 v[182:183], v[182:183], v[148:149] op_sel_hi:[1,0]
	v_pk_fma_f32 v[84:85], v[2:3], v[180:181], v[84:85]
	v_pk_fma_f32 v[86:87], v[4:5], v[182:183], v[86:87]
	global_store_dwordx4 v79, v[84:87], s[10:11] offset:0 nt
	v_pk_mul_f32 v[184:185], v[184:185], v[148:149] op_sel_hi:[1,0]
	v_pk_mul_f32 v[186:187], v[186:187], v[148:149] op_sel_hi:[1,0]
	v_pk_fma_f32 v[88:89], v[6:7], v[184:185], v[88:89]
	v_pk_fma_f32 v[90:91], v[8:9], v[186:187], v[90:91]
	global_store_dwordx4 v79, v[88:91], s[10:11] offset:1024 nt
	v_pk_mul_f32 v[188:189], v[188:189], v[148:149] op_sel_hi:[1,0]
	v_pk_mul_f32 v[190:191], v[190:191], v[148:149] op_sel_hi:[1,0]
	v_pk_fma_f32 v[92:93], v[10:11], v[188:189], v[92:93]
	v_pk_fma_f32 v[94:95], v[12:13], v[190:191], v[94:95]
	global_store_dwordx4 v79, v[92:95], s[10:11] offset:2048 nt
	v_pk_mul_f32 v[192:193], v[192:193], v[148:149] op_sel_hi:[1,0]
	v_pk_mul_f32 v[194:195], v[194:195], v[148:149] op_sel_hi:[1,0]
	v_pk_fma_f32 v[96:97], v[14:15], v[192:193], v[96:97]
	v_pk_fma_f32 v[98:99], v[16:17], v[194:195], v[98:99]
	global_store_dwordx4 v79, v[96:99], s[10:11] offset:3072 nt
	s_add_u32 s2, s21, 1
	s_lshl_b32 s2, s2, 12
	s_add_u32 s10, s72, s2
	s_addc_u32 s11, s73, 0
	v_pk_mul_f32 v[196:197], v[196:197], v[156:157] op_sel_hi:[1,0]
	v_pk_mul_f32 v[198:199], v[198:199], v[156:157] op_sel_hi:[1,0]
	v_pk_fma_f32 v[100:101], v[2:3], v[196:197], v[100:101]
	v_pk_fma_f32 v[102:103], v[4:5], v[198:199], v[102:103]
	global_store_dwordx4 v79, v[100:103], s[10:11] offset:0 nt
	v_pk_mul_f32 v[200:201], v[200:201], v[156:157] op_sel_hi:[1,0]
	v_pk_mul_f32 v[202:203], v[202:203], v[156:157] op_sel_hi:[1,0]
	v_pk_fma_f32 v[104:105], v[6:7], v[200:201], v[104:105]
	v_pk_fma_f32 v[106:107], v[8:9], v[202:203], v[106:107]
	global_store_dwordx4 v79, v[104:107], s[10:11] offset:1024 nt
	v_pk_mul_f32 v[204:205], v[204:205], v[156:157] op_sel_hi:[1,0]
	v_pk_mul_f32 v[206:207], v[206:207], v[156:157] op_sel_hi:[1,0]
	v_pk_fma_f32 v[108:109], v[10:11], v[204:205], v[108:109]
	v_pk_fma_f32 v[110:111], v[12:13], v[206:207], v[110:111]
	global_store_dwordx4 v79, v[108:111], s[10:11] offset:2048 nt
	v_pk_mul_f32 v[208:209], v[208:209], v[156:157] op_sel_hi:[1,0]
	v_pk_mul_f32 v[210:211], v[210:211], v[156:157] op_sel_hi:[1,0]
	v_pk_fma_f32 v[112:113], v[14:15], v[208:209], v[112:113]
	v_pk_fma_f32 v[114:115], v[16:17], v[210:211], v[114:115]
	global_store_dwordx4 v79, v[112:115], s[10:11] offset:3072 nt
	s_nop 1
	s_add_u32 s2, s21, 2
	s_mul_i32 s12, s2, 0x3000
	s_add_u32 s10, s74, 0x39c4000
	s_addc_u32 s11, s75, 0
	s_add_u32 s10, s10, s12
	s_addc_u32 s11, s11, 0
	global_load_dwordx2 v[148:149], v80, s[10:11] offset:0 nt
	global_load_dwordx2 v[150:151], v80, s[10:11] offset:512 nt
	global_load_dwordx2 v[152:153], v80, s[10:11] offset:1024 nt
	global_load_dwordx2 v[154:155], v80, s[10:11] offset:1536 nt
	s_cmpk_lt_u32 s2, 0x2000
	s_cselect_b32 s10, s4, s6
	s_cselect_b32 s11, s5, s7
	s_and_b32 s12, s2, 0x1fff
	s_lshl_b32 s12, s12, 12
	s_add_u32 s10, s10, s12
	s_addc_u32 s11, s11, 0
	global_load_dwordx4 v[84:87], v79, s[10:11] offset:0 nt
	global_load_dwordx4 v[88:91], v79, s[10:11] offset:1024 nt
	global_load_dwordx4 v[92:95], v79, s[10:11] offset:2048 nt
	global_load_dwordx4 v[96:99], v79, s[10:11] offset:3072 nt
	s_cmp_eq_u32 s28, 0
	s_cbranch_scc1 .Lp7n_nocol_b2
	s_and_b32 s12, s2, 63
	s_lshl_b32 s12, s12, 10
	s_add_u32 s10, s74, 0x94000
	s_addc_u32 s11, s75, 0
	s_add_u32 s10, s10, s12
	s_addc_u32 s11, s11, 0
	global_load_dwordx4 v[18:21], v79, s[10:11]
	s_add_u32 s10, s10, 0x10000
	s_addc_u32 s11, s11, 0
	global_load_dwordx4 v[22:25], v79, s[10:11]
.Lp7n_nocol_b2:
	s_add_u32 s2, s21, 3
	s_mul_i32 s12, s2, 0x3000
	s_add_u32 s10, s74, 0x39c4000
	s_addc_u32 s11, s75, 0
	s_add_u32 s10, s10, s12
	s_addc_u32 s11, s11, 0
	global_load_dwordx2 v[156:157], v80, s[10:11] offset:0 nt
	global_load_dwordx2 v[158:159], v80, s[10:11] offset:512 nt
	global_load_dwordx2 v[160:161], v80, s[10:11] offset:1024 nt
	global_load_dwordx2 v[162:163], v80, s[10:11] offset:1536 nt
	s_cmpk_lt_u32 s2, 0x2000
	s_cselect_b32 s10, s4, s6
	s_cselect_b32 s11, s5, s7
	s_and_b32 s12, s2, 0x1fff
	s_lshl_b32 s12, s12, 12
	s_add_u32 s10, s10, s12
	s_addc_u32 s11, s11, 0
	global_load_dwordx4 v[100:103], v79, s[10:11] offset:0 nt
	global_load_dwordx4 v[104:107], v79, s[10:11] offset:1024 nt
	global_load_dwordx4 v[108:111], v79, s[10:11] offset:2048 nt
	global_load_dwordx4 v[112:115], v79, s[10:11] offset:3072 nt
	s_cmp_eq_u32 s28, 0
	s_cbranch_scc1 .Lp7n_nocol_b3
	s_and_b32 s12, s2, 63
	s_lshl_b32 s12, s12, 10
	s_add_u32 s10, s74, 0x94000
	s_addc_u32 s11, s75, 0
	s_add_u32 s10, s10, s12
	s_addc_u32 s11, s11, 0
	global_load_dwordx4 v[26:29], v79, s[10:11]
	s_add_u32 s10, s10, 0x10000
	s_addc_u32 s11, s11, 0
	global_load_dwordx4 v[30:33], v79, s[10:11]
.Lp7n_nocol_b3:
	s_add_u32 s2, s21, 4
	s_mul_i32 s12, s2, 0x3000
	s_add_u32 s10, s74, 0x39c4000
	s_addc_u32 s11, s75, 0
	s_add_u32 s10, s10, s12
	s_addc_u32 s11, s11, 0
	global_load_dwordx2 v[164:165], v80, s[10:11] offset:0 nt
	global_load_dwordx2 v[166:167], v80, s[10:11] offset:512 nt
	global_load_dwordx2 v[168:169], v80, s[10:11] offset:1024 nt
	global_load_dwordx2 v[170:171], v80, s[10:11] offset:1536 nt
	s_cmpk_lt_u32 s2, 0x2000
	s_cselect_b32 s10, s4, s6
	s_cselect_b32 s11, s5, s7
	s_and_b32 s12, s2, 0x1fff
	s_lshl_b32 s12, s12, 12
	s_add_u32 s10, s10, s12
	s_addc_u32 s11, s11, 0
	global_load_dwordx4 v[116:119], v79, s[10:11] offset:0 nt
	global_load_dwordx4 v[120:123], v79, s[10:11] offset:1024 nt
	global_load_dwordx4 v[124:127], v79, s[10:11] offset:2048 nt
	global_load_dwordx4 v[128:131], v79, s[10:11] offset:3072 nt
	s_cmp_eq_u32 s28, 0
	s_cbranch_scc1 .Lp7n_nocol_b4
	s_and_b32 s12, s2, 63
	s_lshl_b32 s12, s12, 10
	s_add_u32 s10, s74, 0x94000
	s_addc_u32 s11, s75, 0
	s_add_u32 s10, s10, s12
	s_addc_u32 s11, s11, 0
	global_load_dwordx4 v[46:49], v79, s[10:11]
	s_add_u32 s10, s10, 0x10000
	s_addc_u32 s11, s11, 0
	global_load_dwordx4 v[50:53], v79, s[10:11]
.Lp7n_nocol_b4:
	s_add_u32 s2, s21, 5
	s_mul_i32 s12, s2, 0x3000
	s_add_u32 s10, s74, 0x39c4000
	s_addc_u32 s11, s75, 0
	s_add_u32 s10, s10, s12
	s_addc_u32 s11, s11, 0
	global_load_dwordx2 v[172:173], v80, s[10:11] offset:0 nt
	global_load_dwordx2 v[174:175], v80, s[10:11] offset:512 nt
	global_load_dwordx2 v[176:177], v80, s[10:11] offset:1024 nt
	global_load_dwordx2 v[178:179], v80, s[10:11] offset:1536 nt
	s_cmpk_lt_u32 s2, 0x2000
	s_cselect_b32 s10, s4, s6
	s_cselect_b32 s11, s5, s7
	s_and_b32 s12, s2, 0x1fff
	s_lshl_b32 s12, s12, 12
	s_add_u32 s10, s10, s12
	s_addc_u32 s11, s11, 0
	global_load_dwordx4 v[132:135], v79, s[10:11] offset:0 nt
	global_load_dwordx4 v[136:139], v79, s[10:11] offset:1024 nt
	global_load_dwordx4 v[140:143], v79, s[10:11] offset:2048 nt
	global_load_dwordx4 v[144:147], v79, s[10:11] offset:3072 nt
	s_cmp_eq_u32 s28, 0
	s_cbranch_scc1 .Lp7n_nocol_b5
	s_and_b32 s12, s2, 63
	s_lshl_b32 s12, s12, 10
	s_add_u32 s10, s74, 0x94000
	s_addc_u32 s11, s75, 0
	s_add_u32 s10, s10, s12
	s_addc_u32 s11, s11, 0
	global_load_dwordx4 v[54:57], v79, s[10:11]
	s_add_u32 s10, s10, 0x10000
	s_addc_u32 s11, s11, 0
	global_load_dwordx4 v[58:61], v79, s[10:11]

.Lp7n_nope_b1:
	v_lshlrev_b32_e32 v180, 16, v148
	v_and_b32_e32 v181, 0xffff0000, v148
	v_lshlrev_b32_e32 v182, 16, v149
	v_and_b32_e32 v183, 0xffff0000, v149
	v_lshlrev_b32_e32 v184, 16, v150
	v_and_b32_e32 v185, 0xffff0000, v150
	v_lshlrev_b32_e32 v186, 16, v151
	v_and_b32_e32 v187, 0xffff0000, v151
	v_lshlrev_b32_e32 v188, 16, v152
	v_and_b32_e32 v189, 0xffff0000, v152
	v_lshlrev_b32_e32 v190, 16, v153
	v_and_b32_e32 v191, 0xffff0000, v153
	v_lshlrev_b32_e32 v192, 16, v154
	v_and_b32_e32 v193, 0xffff0000, v154
	v_lshlrev_b32_e32 v194, 16, v155
	v_and_b32_e32 v195, 0xffff0000, v155
	v_lshlrev_b32_e32 v196, 16, v156
	v_and_b32_e32 v197, 0xffff0000, v156
	v_lshlrev_b32_e32 v198, 16, v157
	v_and_b32_e32 v199, 0xffff0000, v157
	v_lshlrev_b32_e32 v200, 16, v158
	v_and_b32_e32 v201, 0xffff0000, v158
	v_lshlrev_b32_e32 v202, 16, v159
	v_and_b32_e32 v203, 0xffff0000, v159
	v_lshlrev_b32_e32 v204, 16, v160
	v_and_b32_e32 v205, 0xffff0000, v160
	v_lshlrev_b32_e32 v206, 16, v161
	v_and_b32_e32 v207, 0xffff0000, v161
	v_lshlrev_b32_e32 v208, 16, v162
	v_and_b32_e32 v209, 0xffff0000, v162
	v_lshlrev_b32_e32 v210, 16, v163
	v_and_b32_e32 v211, 0xffff0000, v163
	v_lshlrev_b32_e32 v212, 16, v164
	v_and_b32_e32 v213, 0xffff0000, v164
	v_lshlrev_b32_e32 v214, 16, v165
	v_and_b32_e32 v215, 0xffff0000, v165
	v_lshlrev_b32_e32 v216, 16, v166
	v_and_b32_e32 v217, 0xffff0000, v166
	v_lshlrev_b32_e32 v218, 16, v167
	v_and_b32_e32 v219, 0xffff0000, v167
	v_lshlrev_b32_e32 v220, 16, v168
	v_and_b32_e32 v221, 0xffff0000, v168
	v_lshlrev_b32_e32 v222, 16, v169
	v_and_b32_e32 v223, 0xffff0000, v169
	v_lshlrev_b32_e32 v224, 16, v170
	v_and_b32_e32 v225, 0xffff0000, v170
	v_lshlrev_b32_e32 v226, 16, v171
	v_and_b32_e32 v227, 0xffff0000, v171
	v_lshlrev_b32_e32 v228, 16, v172
	v_and_b32_e32 v229, 0xffff0000, v172
	v_lshlrev_b32_e32 v230, 16, v173
	v_and_b32_e32 v231, 0xffff0000, v173
	v_lshlrev_b32_e32 v232, 16, v174
	v_and_b32_e32 v233, 0xffff0000, v174
	v_lshlrev_b32_e32 v234, 16, v175
	v_and_b32_e32 v235, 0xffff0000, v175
	v_lshlrev_b32_e32 v236, 16, v176
	v_and_b32_e32 v237, 0xffff0000, v176
	v_lshlrev_b32_e32 v238, 16, v177
	v_and_b32_e32 v239, 0xffff0000, v177
	v_lshlrev_b32_e32 v240, 16, v178
	v_and_b32_e32 v241, 0xffff0000, v178
	v_lshlrev_b32_e32 v242, 16, v179
	v_and_b32_e32 v243, 0xffff0000, v179
	v_pk_mul_f32 v[148:149], v[180:181], v[180:181]
	v_pk_mul_f32 v[156:157], v[196:197], v[196:197]
	v_pk_mul_f32 v[164:165], v[212:213], v[212:213]
	v_pk_mul_f32 v[172:173], v[228:229], v[228:229]
	v_pk_fma_f32 v[148:149], v[182:183], v[182:183], v[148:149]
	v_pk_fma_f32 v[156:157], v[198:199], v[198:199], v[156:157]
	v_pk_fma_f32 v[164:165], v[214:215], v[214:215], v[164:165]
	v_pk_fma_f32 v[172:173], v[230:231], v[230:231], v[172:173]
	v_pk_fma_f32 v[148:149], v[184:185], v[184:185], v[148:149]
	v_pk_fma_f32 v[156:157], v[200:201], v[200:201], v[156:157]
	v_pk_fma_f32 v[164:165], v[216:217], v[216:217], v[164:165]
	v_pk_fma_f32 v[172:173], v[232:233], v[232:233], v[172:173]
	v_pk_fma_f32 v[148:149], v[186:187], v[186:187], v[148:149]
	v_pk_fma_f32 v[156:157], v[202:203], v[202:203], v[156:157]
	v_pk_fma_f32 v[164:165], v[218:219], v[218:219], v[164:165]
	v_pk_fma_f32 v[172:173], v[234:235], v[234:235], v[172:173]
	v_pk_fma_f32 v[148:149], v[188:189], v[188:189], v[148:149]
	v_pk_fma_f32 v[156:157], v[204:205], v[204:205], v[156:157]
	v_pk_fma_f32 v[164:165], v[220:221], v[220:221], v[164:165]
	v_pk_fma_f32 v[172:173], v[236:237], v[236:237], v[172:173]
	v_pk_fma_f32 v[148:149], v[190:191], v[190:191], v[148:149]
	v_pk_fma_f32 v[156:157], v[206:207], v[206:207], v[156:157]
	v_pk_fma_f32 v[164:165], v[222:223], v[222:223], v[164:165]
	v_pk_fma_f32 v[172:173], v[238:239], v[238:239], v[172:173]
	v_pk_fma_f32 v[148:149], v[192:193], v[192:193], v[148:149]
	v_pk_fma_f32 v[156:157], v[208:209], v[208:209], v[156:157]
	v_pk_fma_f32 v[164:165], v[224:225], v[224:225], v[164:165]
	v_pk_fma_f32 v[172:173], v[240:241], v[240:241], v[172:173]
	v_pk_fma_f32 v[148:149], v[194:195], v[194:195], v[148:149]
	v_pk_fma_f32 v[156:157], v[210:211], v[210:211], v[156:157]
	v_pk_fma_f32 v[164:165], v[226:227], v[226:227], v[164:165]
	v_pk_fma_f32 v[172:173], v[242:243], v[242:243], v[172:173]
	v_add_f32_e32 v148, v148, v149
	v_add_f32_e32 v156, v156, v157
	v_add_f32_e32 v164, v164, v165
	v_add_f32_e32 v172, v172, v173
	ds_bpermute_b32 v149, v35, v148
	ds_bpermute_b32 v157, v35, v156
	ds_bpermute_b32 v165, v35, v164
	ds_bpermute_b32 v173, v35, v172
	s_waitcnt lgkmcnt(0)
	v_add_f32_e32 v148, v148, v149
	v_add_f32_e32 v156, v156, v157
	v_add_f32_e32 v164, v164, v165
	v_add_f32_e32 v172, v172, v173
	ds_bpermute_b32 v149, v70, v148
	ds_bpermute_b32 v157, v70, v156
	ds_bpermute_b32 v165, v70, v164
	ds_bpermute_b32 v173, v70, v172
	s_waitcnt lgkmcnt(0)
	v_add_f32_e32 v148, v148, v149
	v_add_f32_e32 v156, v156, v157
	v_add_f32_e32 v164, v164, v165
	v_add_f32_e32 v172, v172, v173
	ds_bpermute_b32 v149, v71, v148
	ds_bpermute_b32 v157, v71, v156
	ds_bpermute_b32 v165, v71, v164
	ds_bpermute_b32 v173, v71, v172
	s_waitcnt lgkmcnt(0)
	v_add_f32_e32 v148, v148, v149
	v_add_f32_e32 v156, v156, v157
	v_add_f32_e32 v164, v164, v165
	v_add_f32_e32 v172, v172, v173
	ds_bpermute_b32 v149, v72, v148
	ds_bpermute_b32 v157, v72, v156
	ds_bpermute_b32 v165, v72, v164
	ds_bpermute_b32 v173, v72, v172
	s_waitcnt lgkmcnt(0)
	v_add_f32_e32 v148, v148, v149
	v_add_f32_e32 v156, v156, v157
	v_add_f32_e32 v164, v164, v165
	v_add_f32_e32 v172, v172, v173
	ds_bpermute_b32 v149, v73, v148
	ds_bpermute_b32 v157, v73, v156
	ds_bpermute_b32 v165, v73, v164
	ds_bpermute_b32 v173, v73, v172
	s_waitcnt lgkmcnt(0)
	v_add_f32_e32 v148, v148, v149
	v_add_f32_e32 v156, v156, v157
	v_add_f32_e32 v164, v164, v165
	v_add_f32_e32 v172, v172, v173
	ds_bpermute_b32 v149, v74, v148
	ds_bpermute_b32 v157, v74, v156
	ds_bpermute_b32 v165, v74, v164
	ds_bpermute_b32 v173, v74, v172
	s_waitcnt lgkmcnt(0)
	v_add_f32_e32 v148, v148, v149
	v_add_f32_e32 v156, v156, v157
	v_add_f32_e32 v164, v164, v165
	v_add_f32_e32 v172, v172, v173
	v_fmamk_f32 v148, v148, 0x3a800000, v77
	v_fmamk_f32 v156, v156, 0x3a800000, v77
	v_fmamk_f32 v164, v164, 0x3a800000, v77
	v_fmamk_f32 v172, v172, 0x3a800000, v77
	v_mul_f32_e32 v150, 0x4b800000, v148
	v_cmp_gt_f32_e32 vcc, s26, v148
	s_nop 1
	v_cndmask_b32_e32 v148, v148, v150, vcc
	v_rsq_f32_e32 v148, v148
	s_nop 0
	v_mul_f32_e32 v150, 0x45800000, v148
	v_cndmask_b32_e32 v148, v148, v150, vcc
	v_mul_f32_e32 v158, 0x4b800000, v156
	v_cmp_gt_f32_e32 vcc, s26, v156
	s_nop 1
	v_cndmask_b32_e32 v156, v156, v158, vcc
	v_rsq_f32_e32 v156, v156
	s_nop 0
	v_mul_f32_e32 v158, 0x45800000, v156
	v_cndmask_b32_e32 v156, v156, v158, vcc
	v_mul_f32_e32 v166, 0x4b800000, v164
	v_cmp_gt_f32_e32 vcc, s26, v164
	s_nop 1
	v_cndmask_b32_e32 v164, v164, v166, vcc
	v_rsq_f32_e32 v164, v164
	s_nop 0
	v_mul_f32_e32 v166, 0x45800000, v164
	v_cndmask_b32_e32 v164, v164, v166, vcc
	v_mul_f32_e32 v174, 0x4b800000, v172
	v_cmp_gt_f32_e32 vcc, s26, v172
	s_nop 1
	v_cndmask_b32_e32 v172, v172, v174, vcc
	v_rsq_f32_e32 v172, v172
	s_nop 0
	v_mul_f32_e32 v174, 0x45800000, v172
	v_cndmask_b32_e32 v172, v172, v174, vcc
	s_add_u32 s2, s21, 2
	s_lshl_b32 s2, s2, 12
	s_add_u32 s10, s72, s2
	s_addc_u32 s11, s73, 0
	v_pk_mul_f32 v[180:181], v[180:181], v[148:149] op_sel_hi:[1,0]
	v_pk_mul_f32 v[182:183], v[182:183], v[148:149] op_sel_hi:[1,0]
	v_pk_fma_f32 v[84:85], v[2:3], v[180:181], v[84:85]
	v_pk_fma_f32 v[86:87], v[4:5], v[182:183], v[86:87]
	global_store_dwordx4 v79, v[84:87], s[10:11] offset:0 nt
	v_pk_mul_f32 v[184:185], v[184:185], v[148:149] op_sel_hi:[1,0]
	v_pk_mul_f32 v[186:187], v[186:187], v[148:149] op_sel_hi:[1,0]
	v_pk_fma_f32 v[88:89], v[6:7], v[184:185], v[88:89]
	v_pk_fma_f32 v[90:91], v[8:9], v[186:187], v[90:91]
	global_store_dwordx4 v79, v[88:91], s[10:11] offset:1024 nt
	v_pk_mul_f32 v[188:189], v[188:189], v[148:149] op_sel_hi:[1,0]
	v_pk_mul_f32 v[190:191], v[190:191], v[148:149] op_sel_hi:[1,0]
	v_pk_fma_f32 v[92:93], v[10:11], v[188:189], v[92:93]
	v_pk_fma_f32 v[94:95], v[12:13], v[190:191], v[94:95]
	global_store_dwordx4 v79, v[92:95], s[10:11] offset:2048 nt
	v_pk_mul_f32 v[192:193], v[192:193], v[148:149] op_sel_hi:[1,0]
	v_pk_mul_f32 v[194:195], v[194:195], v[148:149] op_sel_hi:[1,0]
	v_pk_fma_f32 v[96:97], v[14:15], v[192:193], v[96:97]
	v_pk_fma_f32 v[98:99], v[16:17], v[194:195], v[98:99]
	global_store_dwordx4 v79, v[96:99], s[10:11] offset:3072 nt
	s_add_u32 s2, s21, 3
	s_lshl_b32 s2, s2, 12
	s_add_u32 s10, s72, s2
	s_addc_u32 s11, s73, 0
	v_pk_mul_f32 v[196:197], v[196:197], v[156:157] op_sel_hi:[1,0]
	v_pk_mul_f32 v[198:199], v[198:199], v[156:157] op_sel_hi:[1,0]
	v_pk_fma_f32 v[100:101], v[2:3], v[196:197], v[100:101]
	v_pk_fma_f32 v[102:103], v[4:5], v[198:199], v[102:103]
	global_store_dwordx4 v79, v[100:103], s[10:11] offset:0 nt
	v_pk_mul_f32 v[200:201], v[200:201], v[156:157] op_sel_hi:[1,0]
	v_pk_mul_f32 v[202:203], v[202:203], v[156:157] op_sel_hi:[1,0]
	v_pk_fma_f32 v[104:105], v[6:7], v[200:201], v[104:105]
	v_pk_fma_f32 v[106:107], v[8:9], v[202:203], v[106:107]
	global_store_dwordx4 v79, v[104:107], s[10:11] offset:1024 nt
	v_pk_mul_f32 v[204:205], v[204:205], v[156:157] op_sel_hi:[1,0]
	v_pk_mul_f32 v[206:207], v[206:207], v[156:157] op_sel_hi:[1,0]
	v_pk_fma_f32 v[108:109], v[10:11], v[204:205], v[108:109]
	v_pk_fma_f32 v[110:111], v[12:13], v[206:207], v[110:111]
	global_store_dwordx4 v79, v[108:111], s[10:11] offset:2048 nt
	v_pk_mul_f32 v[208:209], v[208:209], v[156:157] op_sel_hi:[1,0]
	v_pk_mul_f32 v[210:211], v[210:211], v[156:157] op_sel_hi:[1,0]
	v_pk_fma_f32 v[112:113], v[14:15], v[208:209], v[112:113]
	v_pk_fma_f32 v[114:115], v[16:17], v[210:211], v[114:115]
	global_store_dwordx4 v79, v[112:115], s[10:11] offset:3072 nt
	s_add_u32 s2, s21, 4
	s_lshl_b32 s2, s2, 12
	s_add_u32 s10, s72, s2
	s_addc_u32 s11, s73, 0
	v_pk_mul_f32 v[212:213], v[212:213], v[164:165] op_sel_hi:[1,0]
	v_pk_mul_f32 v[214:215], v[214:215], v[164:165] op_sel_hi:[1,0]
	v_pk_fma_f32 v[116:117], v[2:3], v[212:213], v[116:117]
	v_pk_fma_f32 v[118:119], v[4:5], v[214:215], v[118:119]
	global_store_dwordx4 v79, v[116:119], s[10:11] offset:0 nt
	v_pk_mul_f32 v[216:217], v[216:217], v[164:165] op_sel_hi:[1,0]
	v_pk_mul_f32 v[218:219], v[218:219], v[164:165] op_sel_hi:[1,0]
	v_pk_fma_f32 v[120:121], v[6:7], v[216:217], v[120:121]
	v_pk_fma_f32 v[122:123], v[8:9], v[218:219], v[122:123]
	global_store_dwordx4 v79, v[120:123], s[10:11] offset:1024 nt
	v_pk_mul_f32 v[220:221], v[220:221], v[164:165] op_sel_hi:[1,0]
	v_pk_mul_f32 v[222:223], v[222:223], v[164:165] op_sel_hi:[1,0]
	v_pk_fma_f32 v[124:125], v[10:11], v[220:221], v[124:125]
	v_pk_fma_f32 v[126:127], v[12:13], v[222:223], v[126:127]
	global_store_dwordx4 v79, v[124:127], s[10:11] offset:2048 nt
	v_pk_mul_f32 v[224:225], v[224:225], v[164:165] op_sel_hi:[1,0]
	v_pk_mul_f32 v[226:227], v[226:227], v[164:165] op_sel_hi:[1,0]
	v_pk_fma_f32 v[128:129], v[14:15], v[224:225], v[128:129]
	v_pk_fma_f32 v[130:131], v[16:17], v[226:227], v[130:131]
	global_store_dwordx4 v79, v[128:131], s[10:11] offset:3072 nt
	s_add_u32 s2, s21, 5
	s_lshl_b32 s2, s2, 12
	s_add_u32 s10, s72, s2
	s_addc_u32 s11, s73, 0
	v_pk_mul_f32 v[228:229], v[228:229], v[172:173] op_sel_hi:[1,0]
	v_pk_mul_f32 v[230:231], v[230:231], v[172:173] op_sel_hi:[1,0]
	v_pk_fma_f32 v[132:133], v[2:3], v[228:229], v[132:133]
	v_pk_fma_f32 v[134:135], v[4:5], v[230:231], v[134:135]
	global_store_dwordx4 v79, v[132:135], s[10:11] offset:0 nt
	v_pk_mul_f32 v[232:233], v[232:233], v[172:173] op_sel_hi:[1,0]
	v_pk_mul_f32 v[234:235], v[234:235], v[172:173] op_sel_hi:[1,0]
	v_pk_fma_f32 v[136:137], v[6:7], v[232:233], v[136:137]
	v_pk_fma_f32 v[138:139], v[8:9], v[234:235], v[138:139]
	global_store_dwordx4 v79, v[136:139], s[10:11] offset:1024 nt
	v_pk_mul_f32 v[236:237], v[236:237], v[172:173] op_sel_hi:[1,0]
	v_pk_mul_f32 v[238:239], v[238:239], v[172:173] op_sel_hi:[1,0]
	v_pk_fma_f32 v[140:141], v[10:11], v[236:237], v[140:141]
	v_pk_fma_f32 v[142:143], v[12:13], v[238:239], v[142:143]
	global_store_dwordx4 v79, v[140:143], s[10:11] offset:2048 nt
	v_pk_mul_f32 v[240:241], v[240:241], v[172:173] op_sel_hi:[1,0]
	v_pk_mul_f32 v[242:243], v[242:243], v[172:173] op_sel_hi:[1,0]
	v_pk_fma_f32 v[144:145], v[14:15], v[240:241], v[144:145]
	v_pk_fma_f32 v[146:147], v[16:17], v[242:243], v[146:147]
	global_store_dwordx4 v79, v[144:147], s[10:11] offset:3072 nt
	s_nop 1
	s_add_u32 s2, s21, 6
	s_mul_i32 s12, s2, 0x3000
	s_add_u32 s10, s74, 0x39c4000
	s_addc_u32 s11, s75, 0
	s_add_u32 s10, s10, s12
	s_addc_u32 s11, s11, 0
	global_load_dwordx2 v[148:149], v80, s[10:11] offset:0 nt
	global_load_dwordx2 v[150:151], v80, s[10:11] offset:512 nt
	global_load_dwordx2 v[152:153], v80, s[10:11] offset:1024 nt
	global_load_dwordx2 v[154:155], v80, s[10:11] offset:1536 nt
	s_cmpk_lt_u32 s2, 0x2000
	s_cselect_b32 s10, s4, s6
	s_cselect_b32 s11, s5, s7
	s_and_b32 s12, s2, 0x1fff
	s_lshl_b32 s12, s12, 12
	s_add_u32 s10, s10, s12
	s_addc_u32 s11, s11, 0
	global_load_dwordx4 v[84:87], v79, s[10:11] offset:0 nt
	global_load_dwordx4 v[88:91], v79, s[10:11] offset:1024 nt
	global_load_dwordx4 v[92:95], v79, s[10:11] offset:2048 nt
	global_load_dwordx4 v[96:99], v79, s[10:11] offset:3072 nt
	s_cmp_eq_u32 s28, 0
	s_cbranch_scc1 .Lp7n_nocol_b6
	s_and_b32 s12, s2, 63
	s_lshl_b32 s12, s12, 10
	s_add_u32 s10, s74, 0x94000
	s_addc_u32 s11, s75, 0
	s_add_u32 s10, s10, s12
	s_addc_u32 s11, s11, 0
	global_load_dwordx4 v[18:21], v79, s[10:11]
	s_add_u32 s10, s10, 0x10000
	s_addc_u32 s11, s11, 0
	global_load_dwordx4 v[22:25], v79, s[10:11]
.Lp7n_nocol_b6:
	s_add_u32 s2, s21, 7
	s_mul_i32 s12, s2, 0x3000
	s_add_u32 s10, s74, 0x39c4000
	s_addc_u32 s11, s75, 0
	s_add_u32 s10, s10, s12
	s_addc_u32 s11, s11, 0
	global_load_dwordx2 v[156:157], v80, s[10:11] offset:0 nt
	global_load_dwordx2 v[158:159], v80, s[10:11] offset:512 nt
	global_load_dwordx2 v[160:161], v80, s[10:11] offset:1024 nt
	global_load_dwordx2 v[162:163], v80, s[10:11] offset:1536 nt
	s_cmpk_lt_u32 s2, 0x2000
	s_cselect_b32 s10, s4, s6
	s_cselect_b32 s11, s5, s7
	s_and_b32 s12, s2, 0x1fff
	s_lshl_b32 s12, s12, 12
	s_add_u32 s10, s10, s12
	s_addc_u32 s11, s11, 0
	global_load_dwordx4 v[100:103], v79, s[10:11] offset:0 nt
	global_load_dwordx4 v[104:107], v79, s[10:11] offset:1024 nt
	global_load_dwordx4 v[108:111], v79, s[10:11] offset:2048 nt
	global_load_dwordx4 v[112:115], v79, s[10:11] offset:3072 nt
	s_cmp_eq_u32 s28, 0
	s_cbranch_scc1 .Lp7n_nocol_b7
	s_and_b32 s12, s2, 63
	s_lshl_b32 s12, s12, 10
	s_add_u32 s10, s74, 0x94000
	s_addc_u32 s11, s75, 0
	s_add_u32 s10, s10, s12
	s_addc_u32 s11, s11, 0
	global_load_dwordx4 v[26:29], v79, s[10:11]
	s_add_u32 s10, s10, 0x10000
	s_addc_u32 s11, s11, 0
	global_load_dwordx4 v[30:33], v79, s[10:11]

.Lp7n_nope_b2:
	v_lshlrev_b32_e32 v180, 16, v148
	v_and_b32_e32 v181, 0xffff0000, v148
	v_lshlrev_b32_e32 v182, 16, v149
	v_and_b32_e32 v183, 0xffff0000, v149
	v_lshlrev_b32_e32 v184, 16, v150
	v_and_b32_e32 v185, 0xffff0000, v150
	v_lshlrev_b32_e32 v186, 16, v151
	v_and_b32_e32 v187, 0xffff0000, v151
	v_lshlrev_b32_e32 v188, 16, v152
	v_and_b32_e32 v189, 0xffff0000, v152
	v_lshlrev_b32_e32 v190, 16, v153
	v_and_b32_e32 v191, 0xffff0000, v153
	v_lshlrev_b32_e32 v192, 16, v154
	v_and_b32_e32 v193, 0xffff0000, v154
	v_lshlrev_b32_e32 v194, 16, v155
	v_and_b32_e32 v195, 0xffff0000, v155
	v_lshlrev_b32_e32 v196, 16, v156
	v_and_b32_e32 v197, 0xffff0000, v156
	v_lshlrev_b32_e32 v198, 16, v157
	v_and_b32_e32 v199, 0xffff0000, v157
	v_lshlrev_b32_e32 v200, 16, v158
	v_and_b32_e32 v201, 0xffff0000, v158
	v_lshlrev_b32_e32 v202, 16, v159
	v_and_b32_e32 v203, 0xffff0000, v159
	v_lshlrev_b32_e32 v204, 16, v160
	v_and_b32_e32 v205, 0xffff0000, v160
	v_lshlrev_b32_e32 v206, 16, v161
	v_and_b32_e32 v207, 0xffff0000, v161
	v_lshlrev_b32_e32 v208, 16, v162
	v_and_b32_e32 v209, 0xffff0000, v162
	v_lshlrev_b32_e32 v210, 16, v163
	v_and_b32_e32 v211, 0xffff0000, v163
	v_pk_mul_f32 v[148:149], v[180:181], v[180:181]
	v_pk_mul_f32 v[156:157], v[196:197], v[196:197]
	v_pk_fma_f32 v[148:149], v[182:183], v[182:183], v[148:149]
	v_pk_fma_f32 v[156:157], v[198:199], v[198:199], v[156:157]
	v_pk_fma_f32 v[148:149], v[184:185], v[184:185], v[148:149]
	v_pk_fma_f32 v[156:157], v[200:201], v[200:201], v[156:157]
	v_pk_fma_f32 v[148:149], v[186:187], v[186:187], v[148:149]
	v_pk_fma_f32 v[156:157], v[202:203], v[202:203], v[156:157]
	v_pk_fma_f32 v[148:149], v[188:189], v[188:189], v[148:149]
	v_pk_fma_f32 v[156:157], v[204:205], v[204:205], v[156:157]
	v_pk_fma_f32 v[148:149], v[190:191], v[190:191], v[148:149]
	v_pk_fma_f32 v[156:157], v[206:207], v[206:207], v[156:157]
	v_pk_fma_f32 v[148:149], v[192:193], v[192:193], v[148:149]
	v_pk_fma_f32 v[156:157], v[208:209], v[208:209], v[156:157]
	v_pk_fma_f32 v[148:149], v[194:195], v[194:195], v[148:149]
	v_pk_fma_f32 v[156:157], v[210:211], v[210:211], v[156:157]
	v_add_f32_e32 v148, v148, v149
	v_add_f32_e32 v156, v156, v157
	ds_bpermute_b32 v149, v35, v148
	ds_bpermute_b32 v157, v35, v156
	s_waitcnt lgkmcnt(0)
	v_add_f32_e32 v148, v148, v149
	v_add_f32_e32 v156, v156, v157
	ds_bpermute_b32 v149, v70, v148
	ds_bpermute_b32 v157, v70, v156
	s_waitcnt lgkmcnt(0)
	v_add_f32_e32 v148, v148, v149
	v_add_f32_e32 v156, v156, v157
	ds_bpermute_b32 v149, v71, v148
	ds_bpermute_b32 v157, v71, v156
	s_waitcnt lgkmcnt(0)
	v_add_f32_e32 v148, v148, v149
	v_add_f32_e32 v156, v156, v157
	ds_bpermute_b32 v149, v72, v148
	ds_bpermute_b32 v157, v72, v156
	s_waitcnt lgkmcnt(0)
	v_add_f32_e32 v148, v148, v149
	v_add_f32_e32 v156, v156, v157
	ds_bpermute_b32 v149, v73, v148
	ds_bpermute_b32 v157, v73, v156
	s_waitcnt lgkmcnt(0)
	v_add_f32_e32 v148, v148, v149
	v_add_f32_e32 v156, v156, v157
	ds_bpermute_b32 v149, v74, v148
	ds_bpermute_b32 v157, v74, v156
	s_waitcnt lgkmcnt(0)
	v_add_f32_e32 v148, v148, v149
	v_add_f32_e32 v156, v156, v157
	v_fmamk_f32 v148, v148, 0x3a800000, v77
	v_fmamk_f32 v156, v156, 0x3a800000, v77
	v_mul_f32_e32 v150, 0x4b800000, v148
	v_cmp_gt_f32_e32 vcc, s26, v148
	s_nop 1
	v_cndmask_b32_e32 v148, v148, v150, vcc
	v_rsq_f32_e32 v148, v148
	s_nop 0
	v_mul_f32_e32 v150, 0x45800000, v148
	v_cndmask_b32_e32 v148, v148, v150, vcc
	v_mul_f32_e32 v158, 0x4b800000, v156
	v_cmp_gt_f32_e32 vcc, s26, v156
	s_nop 1
	v_cndmask_b32_e32 v156, v156, v158, vcc
	v_rsq_f32_e32 v156, v156
	s_nop 0
	v_mul_f32_e32 v158, 0x45800000, v156
	v_cndmask_b32_e32 v156, v156, v158, vcc
	s_add_u32 s2, s21, 6
	s_lshl_b32 s2, s2, 12
	s_add_u32 s10, s72, s2
	s_addc_u32 s11, s73, 0
	v_pk_mul_f32 v[180:181], v[180:181], v[148:149] op_sel_hi:[1,0]
	v_pk_mul_f32 v[182:183], v[182:183], v[148:149] op_sel_hi:[1,0]
	v_pk_fma_f32 v[84:85], v[2:3], v[180:181], v[84:85]
	v_pk_fma_f32 v[86:87], v[4:5], v[182:183], v[86:87]
	global_store_dwordx4 v79, v[84:87], s[10:11] offset:0 nt
	v_pk_mul_f32 v[184:185], v[184:185], v[148:149] op_sel_hi:[1,0]
	v_pk_mul_f32 v[186:187], v[186:187], v[148:149] op_sel_hi:[1,0]
	v_pk_fma_f32 v[88:89], v[6:7], v[184:185], v[88:89]
	v_pk_fma_f32 v[90:91], v[8:9], v[186:187], v[90:91]
	global_store_dwordx4 v79, v[88:91], s[10:11] offset:1024 nt
	v_pk_mul_f32 v[188:189], v[188:189], v[148:149] op_sel_hi:[1,0]
	v_pk_mul_f32 v[190:191], v[190:191], v[148:149] op_sel_hi:[1,0]
	v_pk_fma_f32 v[92:93], v[10:11], v[188:189], v[92:93]
	v_pk_fma_f32 v[94:95], v[12:13], v[190:191], v[94:95]
	global_store_dwordx4 v79, v[92:95], s[10:11] offset:2048 nt
	v_pk_mul_f32 v[192:193], v[192:193], v[148:149] op_sel_hi:[1,0]
	v_pk_mul_f32 v[194:195], v[194:195], v[148:149] op_sel_hi:[1,0]
	v_pk_fma_f32 v[96:97], v[14:15], v[192:193], v[96:97]
	v_pk_fma_f32 v[98:99], v[16:17], v[194:195], v[98:99]
	global_store_dwordx4 v79, v[96:99], s[10:11] offset:3072 nt
	s_add_u32 s2, s21, 7
	s_lshl_b32 s2, s2, 12
	s_add_u32 s10, s72, s2
	s_addc_u32 s11, s73, 0
	v_pk_mul_f32 v[196:197], v[196:197], v[156:157] op_sel_hi:[1,0]
	v_pk_mul_f32 v[198:199], v[198:199], v[156:157] op_sel_hi:[1,0]
	v_pk_fma_f32 v[100:101], v[2:3], v[196:197], v[100:101]
	v_pk_fma_f32 v[102:103], v[4:5], v[198:199], v[102:103]
	global_store_dwordx4 v79, v[100:103], s[10:11] offset:0 nt
	v_pk_mul_f32 v[200:201], v[200:201], v[156:157] op_sel_hi:[1,0]
	v_pk_mul_f32 v[202:203], v[202:203], v[156:157] op_sel_hi:[1,0]
	v_pk_fma_f32 v[104:105], v[6:7], v[200:201], v[104:105]
	v_pk_fma_f32 v[106:107], v[8:9], v[202:203], v[106:107]
	global_store_dwordx4 v79, v[104:107], s[10:11] offset:1024 nt
	v_pk_mul_f32 v[204:205], v[204:205], v[156:157] op_sel_hi:[1,0]
	v_pk_mul_f32 v[206:207], v[206:207], v[156:157] op_sel_hi:[1,0]
	v_pk_fma_f32 v[108:109], v[10:11], v[204:205], v[108:109]
	v_pk_fma_f32 v[110:111], v[12:13], v[206:207], v[110:111]
	global_store_dwordx4 v79, v[108:111], s[10:11] offset:2048 nt
	v_pk_mul_f32 v[208:209], v[208:209], v[156:157] op_sel_hi:[1,0]
	v_pk_mul_f32 v[210:211], v[210:211], v[156:157] op_sel_hi:[1,0]
	v_pk_fma_f32 v[112:113], v[14:15], v[208:209], v[112:113]
	v_pk_fma_f32 v[114:115], v[16:17], v[210:211], v[114:115]
	global_store_dwordx4 v79, v[112:115], s[10:11] offset:3072 nt
	s_nop 1
	s_branch .LBB0_1002
